# HGRN finalize phase: next row's loads issued one iteration ahead, gnorm loads hoisted out of the loop
# speedup vs baseline: 1.0802x; 1.0010x over previous
.LBB0_149:
	s_and_b64 vcc, exec, s[0:1]
	s_cbranch_vccz .LBB0_187
	s_waitcnt vmcnt(5)
	v_mov_b32_e32 v4, v159
	v_readlane_b32 s0, v235, 0
	v_mov_b32_e32 v0, v159
	s_lshl_b32 s20, s0, 2
	s_movk_i32 s0, 0x4000
	s_waitcnt lgkmcnt(0)
	v_ashrrev_i32_e32 v2, 6, v0
	v_add_u32_e32 v8, s20, v2
	v_cmp_gt_i32_e32 vcc, s0, v8
	s_and_saveexec_b64 s[0:1], vcc
	v_readlane_b32 s30, v233, 52
	v_readlane_b32 s36, v233, 54
	v_readlane_b32 s28, v233, 56
	v_readlane_b32 s31, v233, 53
	v_readlane_b32 s37, v233, 55
	v_readlane_b32 s29, v233, 57
	s_cbranch_execz .LBB0_153
	s_waitcnt vmcnt(4)
	v_and_b32_e32 v1, 64, v169
	v_xor_b32_e32 v0, 1, v169
	v_add_u32_e32 v1, 64, v1
	v_cmp_lt_i32_e32 vcc, v0, v1
	v_readlane_b32 s24, v232, 27
	s_lshl_b32 s2, s24, 6
	v_cndmask_b32_e32 v0, v169, v0, vcc
	v_lshlrev_b32_e32 v9, 2, v0
	v_xor_b32_e32 v0, 2, v169
	v_cmp_lt_i32_e32 vcc, v0, v1
	v_readlane_b32 s25, v232, 28
	s_and_b32 s24, s2, 0xffffff80
	v_cndmask_b32_e32 v0, v169, v0, vcc
	s_ashr_i32 s25, s24, 31
	v_lshlrev_b32_e32 v10, 2, v0
	v_xor_b32_e32 v0, 4, v169
	s_lshl_b64 s[24:25], s[24:25], 2
	v_cmp_lt_i32_e32 vcc, v0, v1
	s_add_u32 s24, s56, s24
	s_addc_u32 s25, s57, s25
	v_cndmask_b32_e32 v0, v169, v0, vcc
	v_lshlrev_b32_e32 v11, 2, v0
	v_xor_b32_e32 v0, 8, v169
	v_ashrrev_i32_e32 v3, 31, v2
	s_ashr_i32 s21, s20, 31
	v_cmp_lt_i32_e32 vcc, v0, v1
	v_lshl_add_u64 v[6:7], v[2:3], 0, s[20:21]
	v_and_b32_e32 v13, 63, v4
	v_cndmask_b32_e32 v0, v169, v0, vcc
	v_lshlrev_b64 v[2:3], 11, v[6:7]
	v_lshlrev_b32_e32 v14, 4, v13
	v_lshlrev_b32_e32 v12, 2, v0
	v_lshlrev_b32_e32 v0, 5, v4
	v_or_b32_e32 v4, v2, v14
	v_mov_b32_e32 v5, v3
	s_mov_b64 s[20:21], 0x60fd400
	v_lshlrev_b64 v[6:7], 10, v[6:7]
	v_and_b32_e32 v32, 0x1e0, v0
	v_lshl_add_u64 v[4:5], v[4:5], 0, s[20:21]
	v_or_b32_e32 v6, v6, v14
	s_mov_b64 s[20:21], 0xb4fd000
	v_lshl_add_u64 v[0:1], s[24:25], 0, v[32:33]
	v_lshl_add_u64 v[6:7], v[6:7], 0, s[20:21]
	v_lshl_or_b32 v2, v13, 5, v2
	s_mov_b64 s[20:21], 0
	global_load_dwordx4 v[80:83], v[0:1], off
	global_load_dwordx4 v[84:87], v[0:1], off offset:16
	v_lshl_add_u64 v[68:69], s[94:95], 0, v[2:3]
	s_mov_b64 s[24:25], 0x1080d000
	v_lshl_add_u64 v[60:61], v[68:69], 0, s[24:25]
	s_mov_b64 s[24:25], 0x1280d000
	v_lshl_add_u64 v[68:69], v[68:69], 0, s[24:25]
	v_lshl_add_u64 v[76:77], s[94:95], 0, v[6:7]
	global_load_dwordx4 v[64:67], v[60:61], off offset:16
	global_load_dwordx4 v[60:63], v[60:61], off
	global_load_dwordx4 v[72:75], v[68:69], off offset:16
	global_load_dwordx4 v[68:71], v[68:69], off
	global_load_dwordx4 v[76:79], v[76:77], off
	v_add_u32_e32 v8, s28, v8
	v_lshl_add_u64 v[6:7], v[6:7], 0, s[36:37]
	v_lshl_add_u64 v[2:3], v[2:3], 0, s[30:31]
.LBB0_152:
	s_waitcnt vmcnt(0)
	v_mov_b32_e32 v14, v60
	v_mov_b32_e32 v15, v61
	v_mov_b32_e32 v16, v62
	v_mov_b32_e32 v17, v63
	v_mov_b32_e32 v18, v64
	v_mov_b32_e32 v19, v65
	v_mov_b32_e32 v20, v66
	v_mov_b32_e32 v21, v67
	v_mov_b32_e32 v22, v68
	v_mov_b32_e32 v23, v69
	v_mov_b32_e32 v24, v70
	v_mov_b32_e32 v25, v71
	v_mov_b32_e32 v26, v72
	v_mov_b32_e32 v27, v73
	v_mov_b32_e32 v28, v74
	v_mov_b32_e32 v29, v75
	v_mov_b32_e32 v34, v76
	v_mov_b32_e32 v35, v77
	v_mov_b32_e32 v36, v78
	v_mov_b32_e32 v37, v79
	v_cmp_lt_i32_e32 vcc, s51, v8
	s_or_b64 s[20:21], vcc, s[20:21]
	v_lshl_add_u64 v[68:69], s[94:95], 0, v[2:3]
	s_mov_b64 s[24:25], 0x1080d000
	v_lshl_add_u64 v[60:61], v[68:69], 0, s[24:25]
	s_mov_b64 s[24:25], 0x1280d000
	v_lshl_add_u64 v[68:69], v[68:69], 0, s[24:25]
	v_lshl_add_u64 v[76:77], s[94:95], 0, v[6:7]
	global_load_dwordx4 v[64:67], v[60:61], off offset:16
	global_load_dwordx4 v[60:63], v[60:61], off
	global_load_dwordx4 v[72:75], v[68:69], off offset:16
	global_load_dwordx4 v[68:71], v[68:69], off
	global_load_dwordx4 v[76:79], v[76:77], off
	v_add_u32_e32 v8, s28, v8
	v_lshl_add_u64 v[6:7], v[6:7], 0, s[36:37]
	v_lshl_add_u64 v[2:3], v[2:3], 0, s[30:31]
	v_pk_add_f32 v[14:15], v[14:15], v[22:23]
	v_pk_add_f32 v[30:31], v[20:21], v[28:29]
	v_pk_add_f32 v[38:39], v[18:19], v[26:27]
	v_pk_add_f32 v[16:17], v[16:17], v[24:25]
	v_pk_mul_f32 v[24:25], v[14:15], v[14:15]
	v_pk_mul_f32 v[22:23], v[16:17], v[16:17]
	v_add_f32_e32 v13, v24, v25
	v_add_f32_e32 v13, v22, v13
	v_pk_mul_f32 v[42:43], v[38:39], v[38:39]
	v_add_f32_e32 v13, v23, v13
	v_add_f32_e32 v13, v42, v13
	v_pk_mul_f32 v[40:41], v[30:31], v[30:31]
	v_add_f32_e32 v13, v43, v13
	v_add_f32_e32 v13, v40, v13
	v_add_f32_e32 v13, v41, v13
	ds_bpermute_b32 v22, v9, v13
	v_lshlrev_b32_e32 v46, 16, v35
	v_and_b32_e32 v47, 0xffff0000, v35
	v_lshlrev_b32_e32 v48, 16, v34
	v_and_b32_e32 v49, 0xffff0000, v34
	s_waitcnt lgkmcnt(0)
	v_add_f32_e32 v13, v13, v22
	ds_bpermute_b32 v22, v10, v13
	v_lshlrev_b32_e32 v44, 16, v36
	v_and_b32_e32 v45, 0xffff0000, v36
	s_waitcnt lgkmcnt(0)
	v_add_f32_e32 v13, v13, v22
	ds_bpermute_b32 v22, v11, v13
	s_waitcnt lgkmcnt(0)
	v_add_f32_e32 v13, v13, v22
	ds_bpermute_b32 v22, v12, v13
	s_waitcnt lgkmcnt(0)
	v_add_f32_e32 v13, v13, v22
	v_fmamk_f32 v13, v13, 0x3c000000, v158
	v_cmp_gt_f32_e32 vcc, s26, v13
	v_mul_f32_e32 v22, 0x4b800000, v13
	s_nop 0
	v_cndmask_b32_e32 v13, v13, v22, vcc
	v_rsq_f32_e32 v13, v13
	s_nop 0
	v_mul_f32_e32 v22, 0x45800000, v13
	v_cndmask_b32_e32 v22, v13, v22, vcc
	v_pk_mul_f32 v[14:15], v[14:15], v[22:23] op_sel_hi:[1,0]
	v_pk_mul_f32 v[16:17], v[16:17], v[22:23] op_sel_hi:[1,0]
	v_pk_mul_f32 v[14:15], v[80:81], v[14:15]
	v_pk_mul_f32 v[16:17], v[82:83], v[16:17]
	v_pk_mul_f32 v[14:15], v[14:15], v[48:49]
	v_pk_mul_f32 v[16:17], v[16:17], v[46:47]
	v_cvt_pk_bf16_f32 v14, v14, v15
	v_cvt_pk_bf16_f32 v15, v16, v17
	v_pk_mul_f32 v[16:17], v[38:39], v[22:23] op_sel_hi:[1,0]
	v_pk_mul_f32 v[22:23], v[30:31], v[22:23] op_sel_hi:[1,0]
	v_pk_mul_f32 v[16:17], v[84:85], v[16:17]
	v_lshlrev_b32_e32 v18, 16, v37
	v_and_b32_e32 v19, 0xffff0000, v37
	v_pk_mul_f32 v[20:21], v[86:87], v[22:23]
	v_pk_mul_f32 v[16:17], v[16:17], v[44:45]
	v_pk_mul_f32 v[18:19], v[20:21], v[18:19]
	v_cvt_pk_bf16_f32 v16, v16, v17
	v_cvt_pk_bf16_f32 v17, v18, v19
	v_lshl_add_u64 v[18:19], s[94:95], 0, v[4:5]
	v_lshl_add_u64 v[4:5], v[4:5], 0, s[30:31]
	global_store_dwordx4 v[18:19], v[14:17], off
	s_andn2_b64 exec, exec, s[20:21]
	s_cbranch_execnz .LBB0_152
